# up GEMM unit scheduler: tile index -> (row, column) tile by shifts and masks instead of compiled integer divisions (identical mapping for all 1024 indices)
# speedup vs baseline: 1.0034x; 1.0034x over previous
.LBB0_888:
	s_add_i32 s34, s34, 1
	s_mul_i32 s4, s34, s38
	s_mul_hi_u32 s5, s34, s80
	s_add_i32 s5, s5, s4
	s_mul_i32 s4, s34, s80
	s_add_u32 s12, s4, s90
	s_addc_u32 s13, s5, s28
	v_cmp_gt_i64_e32 vcc, s[12:13], v[134:135]
	v_cmp_lt_i64_e64 s[4:5], s[12:13], v[132:133]
	s_cbranch_vccnz .LBB0_894
	s_and_b32 s11, s12, 7
	s_lshr_b32 s6, s12, 3
	s_lshl_b32 s11, s11, 7
	s_add_i32 s6, s6, s11
	s_lshr_b32 s10, s6, 6
	s_lshl_b32 s10, s10, 2
	s_and_b32 s7, s6, 3
	s_add_i32 s10, s10, s7
	s_bfe_u32 s6, s6, 0x40002
